# scan units of the 100 workgroups with the heaviest up-projection load moved to the 100 lightest (two scan units each)
# baseline (speedup 1.0000x reference)
; __device__ __forceinline__ void mlstm_scan(bf16* DC, float* DN, float* SC, int wg, int G, int tid) {
;     for (int unit = wg; unit < 32 * 8; unit += G) {
;         const int chain = unit >> 3, slice = unit & 7;
;         unsigned* dc = (unsigned*)(DC + (size_t)chain * NSTEP * 8192 + slice * 1024) + tid;
.Lscan_late_entry:
	v_mov_b32_e32 v2, v0
	s_mov_b32 s12, s48
	s_cmpk_lt_u32 s12, 100
	s_cbranch_scc1 .Lscan_exit
	s_mov_b32 s101, 0
	v_ashrrev_i32_e32 v3, 31, v2
	v_and_b32_e32 v1, 63, v2
	v_cmp_gt_i32_e64 s[2:3], 64, v2
	v_lshlrev_b32_e32 v4, 2, v1
	v_lshlrev_b64 v[6:7], 2, v[2:3]
	s_mov_b32 s13, s12
	s_branch .LBB0_655
.LBB0_654:
	s_cmp_lg_u32 s101, 0
	s_cbranch_scc1 .Lscan_exit
	s_mov_b32 s101, 1
	s_cmpk_lt_u32 s12, 156
	s_cbranch_scc1 .Lscan_exit
	s_sub_i32 s13, s12, 156
